# R5 QK->SV seam: P-store drain + barrier moved behind the SV phase's first eight LDS-DMA loads (they do not depend on P)
# baseline (speedup 1.0000x reference)
; #define PG8_BAR __builtin_amdgcn_s_barrier()
; template <class Epi, class Sched>
; __device__ __forceinline__ void gemm_phase(LAS unsigned char* lds, const Sched& S, const Epi& E) {
;     ...
;     int sR, sRb, sC2;
;     { int R, C; stage_rc(tid * 16, R, C); sR = R; sRb = (R & ~31) + perm32(R & 31); sC2 = C * 2; }
;     const size_t kstep = (size_t)(BK * 2);
;     const unsigned ldsbase = (unsigned)(size_t)lds + (unsigned)wid * 1024u;
;     const int aoff = lds_byte(wr * 64 + fr, fq * 8), boff = lds_byte(wc * 32 + fr, fq * 8);
;     ...
;     int ui = 0;
;     const char* cA; const char* cB; unsigned hA, hB; int nt; unsigned voffA, voffB;
;     { Unit u0; if (!S.next(0, u0)) return;
;       cA = u0.A; cB = u0.B; hA = (unsigned)HALF * u0.lda2; hB = (unsigned)HALF * u0.ldb2; nt = u0.nt;
;       voffA = (unsigned)(sR * u0.lda2 + sC2); voffB = (unsigned)(sRb * u0.ldb2 + sC2); }
;     f32x4 acc[2][2][4][2];
; #pragma unroll
;     for (int a = 0; a < 2; ++a)
; #pragma unroll
;         for (int b = 0; b < 2; ++b)
; #pragma unroll
;             for (int m = 0; m < 4; ++m)
; #pragma unroll
;                 for (int n = 0; n < 2; ++n) acc[a][b][m][n] = (f32x4){0.f, 0.f, 0.f, 0.f};
;     bf16x8 At[4][2], B0[2][2], B1[2][2];
;     PG8_STAGE(PG8_SB(0, 0), cB, voffB, hB / 2); PG8_STAGE(PG8_SB(0, 1), cB + hB, voffB, hB / 2); PG8_STAGE(PG8_SA(0, 0), cA, voffA, hA / 2); PG8_STAGE(PG8_SA(0, 1), cA + hA, voffA, hA / 2);
;     if (wr == 1) PG8_BAR;
; __global__ void __launch_bounds__(512, 2) fwd_megakernel(Params Parg) {
;     ...
;             __builtin_amdgcn_fence(__ATOMIC_ACQUIRE, "agent");
;             { PHASE_BEGIN
;               bf16_t* pscr = (bf16_t*)(ws + WS_PSCR + (size_t)(bid >> 1) * (256 * D * 2) + (size_t)(bid & 1) * (CH * 2));
;               const int ib = item & 1, h = (item >> 1) & 3, n = item >> 3;
;               SVSched S{(const char*)(ws + WS_KTQK) + ((size_t)(n * CH + ib * 256) * D + h * 256) * 2, (const char*)(ws + WS_SB) + ((size_t)((h * NCH + n) * 512) * 512) * 2,
;                         (const char*)(ws + WS_VT) + ((size_t)((h * NCH + n) * 512) * 512) * 2, (const char*)pscr, item};
;               EpiSV E; E.o = (bf16_t*)pp->out + (size_t)b * L * 2048; E.dec = WSP(float, WS_DEC); gemm_phase(lds, S, E); }
.LBB0_836:
	v_readlane_b32 s0, v254, 62
	v_readlane_b32 s1, v254, 63
	s_mov_b64 s[4:5], s[0:1]
	buffer_inv sc0
	s_load_dwordx4 s[8:11], s[4:5], 0xc8
	s_ashr_i32 s6, s73, 3
	s_lshl_b32 s7, s6, 9
	s_or_b32 s4, s7, s51
	s_ashr_i32 s5, s4, 31
	s_lshl_b32 s12, s72, 9
	s_lshl_b64 s[4:5], s[4:5], 11
	v_mov_b32_e32 v0, v176
	s_waitcnt lgkmcnt(0)
	s_add_u32 s4, s10, s4
	s_addc_u32 s5, s11, s5
	s_add_u32 s34, s4, s12
	v_mov_b32_e32 v0, v176
	s_addc_u32 s35, s5, 0
	s_add_u32 s26, s34, 0x8900000
	v_bfe_i32 v3, v0, 27, 1
	v_lshlrev_b32_e32 v1, 4, v0
	v_lshrrev_b32_e32 v3, 22, v3
	s_addc_u32 s27, s35, 0
	s_lshl_b32 s4, s72, 14
	v_add_u32_e32 v3, v1, v3
	s_add_i32 s4, s4, s7
	v_and_b32_e32 v3, 0xfffffc00, v3
	s_ashr_i32 s5, s4, 31
	v_sub_u32_e32 v1, v1, v3
	s_lshl_b64 s[16:17], s[4:5], 10
	v_ashrrev_i32_e32 v2, 31, v0
	v_lshrrev_b32_e32 v3, 4, v1
	s_add_u32 s7, s10, s16
	v_lshrrev_b32_e32 v2, 26, v2
	v_bitop3_b32 v1, v3, v1, 32 bitop3:0x6c
	s_addc_u32 s24, s11, s17
	v_add_u32_e32 v2, v0, v2
	v_ashrrev_i32_e32 v4, 31, v1
	s_add_u32 s38, s7, 0x10900000
	v_readfirstlane_b32 s22, v0
	v_ashrrev_i32_e32 v2, 6, v2
	v_lshrrev_b32_e32 v4, 26, v4
	s_addc_u32 s39, s24, 0
	s_ashr_i32 s48, s22, 6
	v_lshlrev_b32_e32 v3, 3, v2
	v_add_u32_e32 v4, v1, v4
	v_and_b32_e32 v3, -16, v3
	v_ashrrev_i32_e32 v5, 6, v4
	v_and_b32_e32 v4, 0xc0, v4
	s_lshl_b32 s4, s48, 10
	v_add_u32_e32 v3, v5, v3
	v_sub_u32_e32 v1, v1, v4
	v_and_b32_e32 v5, 3, v5
	s_mov_b32 s5, 0x3fffe0
	s_add_i32 s4, s4, 0
	s_ashr_i32 s23, s22, 8
	v_lshlrev_b32_e32 v2, 5, v2
	v_ashrrev_i16_sdwa v1, v157, sext(v1) dst_sel:DWORD dst_unused:UNUSED_PAD src0_sel:DWORD src1_sel:BYTE_0
	v_lshlrev_b32_e32 v4, 1, v3
	v_lshrrev_b32_e32 v6, 2, v3
	v_and_or_b32 v5, v3, s5, v5
	s_add_i32 s5, s4, 0x10000
	v_bfe_i32 v1, v1, 0, 16
	v_and_b32_e32 v4, 24, v4
	v_and_b32_e32 v6, 4, v6
	v_and_b32_e32 v2, 32, v2
	s_add_u32 s14, s7, 0x10910000
	v_or3_b32 v4, v5, v6, v4
	v_add_lshl_u32 v1, v2, v1, 1
	s_addc_u32 s15, s24, 0
	s_add_i32 s12, s4, 0x12000
	v_lshl_add_u32 v128, v4, 10, v1
	s_mov_b32 m0, s5
	s_nop 0
	global_load_lds_dwordx4 v128, s[38:39]
	s_mov_b32 m0, s12
	s_add_u32 s30, s7, 0x10920000
	global_load_lds_dwordx4 v128, s[14:15]
	s_addc_u32 s31, s24, 0
	s_add_i32 s14, s4, 0x14000
	s_mov_b32 m0, s14
	s_nop 0
	global_load_lds_dwordx4 v128, s[30:31]
	s_add_u32 s30, s7, 0x10930000
	s_addc_u32 s31, s24, 0
	s_add_i32 s15, s4, 0x16000
	s_mov_b32 m0, s15
	s_nop 0
	global_load_lds_dwordx4 v128, s[30:31]
	s_add_u32 s30, s34, 0x8920000
	v_lshl_add_u32 v172, v3, 11, v1
	s_mov_b32 m0, s4
	s_nop 0
	global_load_lds_dwordx4 v172, s[26:27]
	s_addc_u32 s31, s35, 0
	s_add_i32 s24, s4, 0x2000
	s_mov_b32 m0, s24
	s_nop 0
	global_load_lds_dwordx4 v172, s[30:31]
	s_add_u32 s30, s34, 0x8940000
	s_addc_u32 s31, s35, 0
	s_add_i32 s33, s4, 0x4000
	s_mov_b32 m0, s33
	s_nop 0
	global_load_lds_dwordx4 v172, s[30:31]
	s_add_u32 s30, s34, 0x8960000
	s_addc_u32 s31, s35, 0
	s_add_i32 s34, s4, 0x6000
	s_mov_b32 m0, s34
	s_nop 0
	global_load_lds_dwordx4 v172, s[30:31]
	s_cmp_eq_u32 s23, 1
	s_cselect_b64 s[40:41], -1, 0
	s_cmp_lg_u32 s23, 1
	s_waitcnt vmcnt(0)
	s_barrier
	s_cbranch_scc1 .LBB0_838
	s_barrier
